# pipelined prep + scalar-address chain loop + sweep-first after the chain + chain workgroups' first pop without the pre-check load
# baseline (speedup 1.0000x reference)
.LBB0_1046:
	s_lshl_b32 s30, s86, 8
	s_lshl_b64 s[12:13], s[86:87], 3
	s_and_b64 vcc, exec, s[38:39]
	s_lshl_b64 s[14:15], s[86:87], 12
	v_readlane_b32 s47, v254, 58
	s_cbranch_vccnz .LBB0_1097
	s_andn2_b64 vcc, exec, s[8:9]
	s_cbranch_vccnz .LBB0_1084
	s_mov_b64 s[6:7], s[0:1]
	s_waitcnt vmcnt(0)
	s_barrier
	s_and_saveexec_b64 s[4:5], s[10:11]
	s_cbranch_execz .LBB0_1054
	s_load_dwordx2 s[6:7], s[6:7], 0x58
	v_readlane_b32 s8, v254, 12
	s_or_b32 s26, s30, s8
	s_lshl_b64 s[8:9], s[26:27], 2
	v_mov_b32_e32 v0, 0x1a980000
	s_waitcnt lgkmcnt(0)
	s_add_u32 s8, s6, s8
	s_addc_u32 s9, s7, s9
	s_add_u32 s6, s8, 0x1a980000
	s_addc_u32 s7, s9, 0
	v_mov_b32_e32 v0, 64
	s_mov_b64 s[22:23], exec
	v_mbcnt_lo_u32_b32 v0, s22, 0
	v_mbcnt_hi_u32_b32 v0, s23, v0
	v_cmp_eq_u32_e32 vcc, 0, v0
	s_and_saveexec_b64 s[8:9], vcc
	s_cbranch_execz .LBB0_1052
	s_bcnt1_i32_b64 s22, s[22:23]
	v_mov_b32_e32 v1, s22
	global_atomic_add v1, v209, v1, s[6:7] sc0
